# next-tile K/V load addresses in window/attnB/selected-block loops: scalar base + per-thread 32-bit offset (14 VALU fewer per tile)
# baseline (speedup 1.0000x reference)
; DI int tidx() { int t = threadIdx.x; asm volatile("" : "+v"(t)); return t; }
; DI void task_attnA(const P& p, int layer, int task, bf16_t* sm, int dm) {
;     ...
;     const float li = 0.8f - 0.6f * expf(-0.3f * (float)layer);
; DI void kv_gload(KVRegs& r, const bf16_t* kg, size_t kld, const bf16_t* vg, size_t vld, int key0) {
;   const int c0 = tidx();
;   r.k0 = *(const u32x4*)(kg + (size_t)(key0 + (c0 >> 3)) * kld + (c0 & 7) * 8);
;   r.v0 = *(const u32x4*)(vg + (size_t)(c0 >> 3) * vld + key0 + (c0 & 7) * 8);
; }
.LBB0_637:
	s_or_b64 exec, exec, s[0:1]
	v_cvt_f32_u32_e32 v0, s26
	s_mov_b32 s2, 0x3fb8aa3b
	s_lshl_b32 s66, s26, 6
	s_lshl_b64 s[0:1], s[66:67], 2
	v_mul_f32_e32 v0, 0xbe99999a, v0
	v_mul_f32_e32 v1, 0x3fb8aa3b, v0
	v_fma_f32 v2, v0, s2, -v1
	v_rndne_f32_e32 v3, v1
	v_fmac_f32_e32 v2, 0x32a5705f, v0
	v_sub_f32_e32 v1, v1, v3
	v_add_f32_e32 v1, v1, v2
	v_exp_f32_e32 v1, v1
	v_cvt_i32_f32_e32 v2, v3
	v_readlane_b32 s2, v253, 32
	s_add_u32 s62, s2, s0
	v_readlane_b32 s0, v253, 33
	s_addc_u32 s63, s0, s1
	s_lshl_b32 s0, s26, 3
	v_writelane_b32 v255, s0, 15
	s_mov_b32 s0, 0xc2ce8ed0
	v_ldexp_f32 v1, v1, v2
	v_cmp_ngt_f32_e32 vcc, s0, v0
	s_mov_b32 s0, 0x42b17218
	s_lshl_b32 s4, s26, 11
	v_cndmask_b32_e32 v1, 0, v1, vcc
	v_cmp_nlt_f32_e32 vcc, s0, v0
	s_lshl_b32 s66, s26, 7
	s_lshl_b64 s[0:1], s[26:27], 21
	s_lshl_b64 s[2:3], s[26:27], 17
	v_writelane_b32 v255, s4, 21
	s_lshl_b64 s[4:5], s[26:27], 2
	v_readlane_b32 s6, v254, 32
	s_add_u32 s6, s6, s4
	v_readlane_b32 s4, v254, 33
	v_readlane_b32 s36, v253, 6
	s_addc_u32 s7, s4, s5
	s_lshl_b64 s[4:5], s[66:67], 2
	v_readlane_b32 s44, v253, 14
	v_readlane_b32 s45, v253, 15
	s_add_u32 s26, s44, s4
	v_writelane_b32 v255, s6, 23
	s_addc_u32 s27, s45, s5
	v_readlane_b32 s4, v254, 34
	v_writelane_b32 v255, s7, 24
	s_add_u32 s0, s4, s0
	v_writelane_b32 v255, s0, 19
	v_readlane_b32 s0, v254, 35
	v_mov_b32_e32 v0, 0x7f800000
	s_addc_u32 s0, s0, s1
	v_cndmask_b32_e32 v0, v0, v1, vcc
	v_mov_b32_e32 v1, 0xbf4ccccd
	v_writelane_b32 v255, s0, 17
	v_readlane_b32 s0, v254, 40
	v_fmamk_f32 v0, v0, 0x3f19999a, v1
	s_add_u32 s60, s0, s2
	v_readlane_b32 s0, v254, 41
	s_waitcnt vmcnt(24)
	v_add_f32_e32 v136, 1.0, v0
	s_addc_u32 s22, s0, s3
	s_barrier
	v_readlane_b32 s37, v253, 7
	v_readlane_b32 s38, v253, 8
	v_readlane_b32 s39, v253, 9
	v_readlane_b32 s40, v253, 10
	v_readlane_b32 s41, v253, 11
	v_readlane_b32 s42, v253, 12
	v_readlane_b32 s43, v253, 13
	v_readlane_b32 s46, v253, 16
	v_readlane_b32 s47, v253, 17
	v_readlane_b32 s48, v253, 18
	v_readlane_b32 s49, v253, 19
	v_readlane_b32 s50, v253, 20
	v_readlane_b32 s51, v253, 21
	v_lshrrev_b32_e32 v235, 3, v195
	v_and_b32_e32 v222, 7, v195
	v_mul_u32_u24_e32 v235, 0x90, v235
	v_lshl_add_u32 v235, v222, 4, v235
	v_lshrrev_b32_e32 v223, 3, v195
	v_and_b32_e32 v224, 7, v195
	v_lshlrev_b32_e32 v224, 4, v224
	v_lshl_add_u32 v225, v223, 13, v224
	v_lshl_add_u32 v223, v223, 8, v224
	v_mov_b32_e32 v224, v225
	s_branch .LBB0_642

; DI int tidx() { int t = threadIdx.x; asm volatile("" : "+v"(t)); return t; }
; DI void kv_gload(KVRegs& r, const bf16_t* kg, size_t kld, const bf16_t* vg, size_t vld, int key0) {
;   const int c0 = tidx();
;   r.k0 = *(const u32x4*)(kg + (size_t)(key0 + (c0 >> 3)) * kld + (c0 & 7) * 8);
;   r.v0 = *(const u32x4*)(vg + (size_t)(c0 >> 3) * vld + key0 + (c0 & 7) * 8);
; }
; DI void task_nsa(const P& p, int layer, int task, bf16_t* sm, int dm) {
;     ...
;     for (; todo; ++itc) {
;       const int j = __ffsll((long long)todo) - 1;
;       todo &= todo - 1ull;
;       bf16_t* Kl = sm + (itc & 1) * 9216; bf16_t* Vl = Kl + 4608;
;       kv_lstore(R, Kl, Vl);
;       if (todo) kv_gload(R, kg, 128, vg, S_, (__ffsll((long long)todo) - 1) * 64);
.LBB0_718:
	v_lshl_add_u64 v[2:3], v[0:1], 0, -1
	v_and_b32_e32 v98, v2, v0
	v_mov_b32_e32 v2, v195
	s_bitcmp1_b32 s39, 0
	v_and_b32_e32 v99, v3, v1
	s_cselect_b32 s2, 0x4800, 0
	s_add_i32 s45, s2, 0
	v_cmp_eq_u64_e64 s[2:3], 0, v[98:99]
	v_add_u32_e32 v2, s45, v235
	s_and_b64 vcc, exec, s[2:3]
	s_waitcnt vmcnt(0)
	ds_write_b128 v2, v[80:83]
	ds_write_b128 v2, v[84:87] offset:9216
	s_cbranch_vccnz .LBB0_720
	v_ffbl_b32_e32 v3, v99
	v_ffbl_b32_e32 v2, v98
	v_add_u32_e64 v3, v3, 32 clamp
	v_min_u32_e32 v6, v3, v2
	s_nop 0
	v_readfirstlane_b32 s36, v6
	s_nop 3
	s_lshl_b32 s42, s36, 14
	s_lshl_b32 s36, s36, 7
	s_add_u32 s42, s0, s42
	s_addc_u32 s43, s1, 0
	s_add_u32 s36, s6, s36
	s_addc_u32 s37, s7, 0
	global_load_dwordx4 v[80:83], v223, s[42:43]
	global_load_dwordx4 v[84:87], v224, s[36:37]

; DI int tidx() { int t = threadIdx.x; asm volatile("" : "+v"(t)); return t; }
; DI void kv_gload(KVRegs& r, const bf16_t* kg, size_t kld, const bf16_t* vg, size_t vld, int key0) {
;   const int c0 = tidx();
;   r.k0 = *(const u32x4*)(kg + (size_t)(key0 + (c0 >> 3)) * kld + (c0 & 7) * 8);
;   r.v0 = *(const u32x4*)(vg + (size_t)(c0 >> 3) * vld + key0 + (c0 & 7) * 8);
; }
; DI void task_nsa(const P& p, int layer, int task, bf16_t* sm, int dm) {
;     ...
;     for (int kt = kt_lo; kt <= kt_hi; ++kt, ++itc) {
;       bf16_t* Kl = sm + (itc & 1) * 9216; bf16_t* Vl = Kl + 4608;
;       kv_lstore(R, Kl, Vl);
;       if (kt < kt_hi) kv_gload(R, kg, 128, vg, S_, (kt + 1) * 64);
.LBB0_808:
	s_bitcmp1_b32 s39, 0
	s_cselect_b32 s0, 0x4800, 0
	v_mov_b32_e32 v0, v195
	s_add_i32 s25, s0, 0
	s_cmp_ge_i32 s45, s35
	s_cselect_b64 s[8:9], -1, 0
	v_add_u32_e32 v0, s25, v235
	s_and_b64 vcc, exec, s[8:9]
	s_waitcnt vmcnt(0)
	ds_write_b128 v0, v[80:83]
	ds_write_b128 v0, v[84:87] offset:9216
	s_cbranch_vccnz .LBB0_810
	s_ashr_i32 s7, s6, 31
	s_add_i32 s36, s6, 64
	s_lshl_b32 s36, s36, 8
	s_add_u32 s36, s2, s36
	s_addc_u32 s37, s3, 0
	s_lshl_b32 s42, s6, 1
	s_add_u32 s42, s4, s42
	s_addc_u32 s43, s5, 0
	global_load_dwordx4 v[80:83], v223, s[36:37]
	global_load_dwordx4 v[84:87], v224, s[42:43] offset:128

; DI int tidx() { int t = threadIdx.x; asm volatile("" : "+v"(t)); return t; }
; DI void kv_gload(KVRegs& r, const bf16_t* kg, size_t kld, const bf16_t* vg, size_t vld, int key0) {
;   const int c0 = tidx();
;   r.k0 = *(const u32x4*)(kg + (size_t)(key0 + (c0 >> 3)) * kld + (c0 & 7) * 8);
;   r.v0 = *(const u32x4*)(vg + (size_t)(c0 >> 3) * vld + key0 + (c0 & 7) * 8);
; }
; DI void task_attnB(const P& p, int layer, int task, bf16_t* sm, int dm) {
;     ...
;   for (int kt = kt_lo; kt <= kt_hi; ++kt) {
;     bf16_t* Kl = sm + (kt & 1) * 9216; bf16_t* Vl = Kl + 4608;
;     kv_lstore(R, Kl, Vl);
;     if (kt < kt_hi) kv_gload(R, kg, 128, vg, S_, (kt + 1) * 64);
.LBB0_900:
	s_bitcmp1_b32 s30, 0
	s_cselect_b32 s0, 0x4800, 0
	v_mov_b32_e32 v0, v195
	s_add_i32 s31, s0, 0
	s_cmp_ge_i32 s30, s25
	s_cselect_b64 s[8:9], -1, 0
	v_add_u32_e32 v0, s31, v235
	s_and_b64 vcc, exec, s[8:9]
	s_waitcnt vmcnt(0)
	ds_write_b128 v0, v[48:51]
	ds_write_b128 v0, v[52:55] offset:9216
	s_cbranch_vccnz .LBB0_902
	s_ashr_i32 s7, s6, 31
	s_add_i32 s36, s6, 64
	s_lshl_b32 s36, s36, 8
	s_add_u32 s36, s2, s36
	s_addc_u32 s37, s3, 0
	s_lshl_b32 s42, s6, 1
	s_add_u32 s42, s4, s42
	s_addc_u32 s43, s5, 0
	global_load_dwordx4 v[48:51], v223, s[36:37]
	global_load_dwordx4 v[52:55], v224, s[42:43] offset:128
